# phase 1 boundary uses the XCD-hierarchical barrier like every other phase (grid.sync path removed)
# baseline (speedup 1.0000x reference)
.LBB0_11:
	s_add_i32 s2, s17, -1
	s_cmp_lt_u32 s2, 39
	s_mul_i32 s2, s17, 0xcccccccd
	v_alignbit_b32 v0, s2, s2, 1
	s_mov_b32 s2, 0x1999999a
	s_cselect_b64 s[6:7], -1, 0
	v_cmp_gt_u32_e32 vcc, s2, v0
	s_and_b64 s[6:7], s[6:7], vcc
	s_and_b64 vcc, exec, s[6:7]
	s_cbranch_vccnz .LBB0_10
	s_cmp_le_i32 s17, s94
	s_cbranch_scc1 .LBB0_82
	s_cmp_lg_u32 s17, s93
	s_mov_b64 s[6:7], -1
	s_waitcnt lgkmcnt(0)
	s_mov_b64 s[8:9], s[0:1]
	s_waitcnt vmcnt(0)
	s_and_b64 vcc, exec, s[96:97]
	s_barrier
	s_cbranch_vccnz .LBB0_68
	v_mbcnt_lo_u32_b32 v0, -1, 0
	v_mbcnt_hi_u32_b32 v0, -1, v0
	s_nop 0
	v_cmp_eq_u32_e32 vcc, 0, v0
	s_and_saveexec_b64 s[6:7], vcc
	s_cbranch_execz .LBB0_67
	v_readlane_b32 s5, v255, 3
	s_load_dwordx2 s[8:9], s[8:9], 0xb0
	s_getreg_b32 s2, hwreg(HW_REG_XCC_ID, 0, 4)
	v_mov_b32_e32 v0, s5
	s_waitcnt vmcnt(0) expcnt(0) lgkmcnt(0)
	ds_read_b32 v2, v0
	v_readlane_b32 s5, v255, 4
	s_and_b32 s2, s2, 15
	s_waitcnt lgkmcnt(0)
	v_cmp_ne_u32_e32 vcc, 0, v2
	v_mov_b32_e32 v0, s5
	ds_read_b32 v0, v0
	s_cbranch_vccnz .LBB0_31
	s_add_u32 s10, s8, 0x1000
	s_addc_u32 s11, s9, 0
	s_add_u32 s22, s8, 0x1100
	s_addc_u32 s23, s9, 0
	s_add_u32 s28, s8, 0x1200
	s_addc_u32 s29, s9, 0
	s_add_u32 s30, s8, 0x1300
	s_addc_u32 s31, s9, 0
	s_mov_b32 s5, 1
	s_branch .LBB0_19

.LBB0_68:
	s_mov_b64 s[6:7], 0
	s_waitcnt lgkmcnt(0)
	s_barrier
.LBB0_81:
.LBB0_82:
	s_mul_hi_i32 s2, s17, 0x66666667
	s_lshr_b32 s5, s2, 31
	s_ashr_i32 s2, s2, 2
	s_add_i32 s6, s2, s5
	s_mov_b32 s2, s6
	v_writelane_b32 v255, s2, 12
	s_nop 1
	v_writelane_b32 v255, s3, 13
	s_mul_i32 s2, s6, 10
	s_sub_i32 s2, s17, s2
	s_cmp_lg_u32 s17, 40
	s_cselect_b32 s5, s2, 10
	s_cmp_lg_u32 s5, 0
	s_cbranch_scc0 .LBB0_85
	s_cmp_lt_i32 s5, 8
	s_cbranch_scc1 .LBB0_86
	s_cmp_lg_u32 s5, 8
	s_waitcnt lgkmcnt(0)
	s_mov_b64 s[6:7], -1
	s_cselect_b64 s[8:9], -1, 0
	s_cbranch_execz .LBB0_87
	s_branch .LBB0_88
